# S2 balanced LDS-DMA issue (2 stages per phase) in MLP2 K-loop only
# baseline (speedup 1.0000x reference)
; #define PG8_STAGE(bufoff, gbase, voff) do { _Pragma("unroll") for (int _i = 0; _i < 2; ++_i) \
;         __builtin_amdgcn_global_load_lds((const unsigned*)((const char*)(gbase) + (voff)[_i]), (LAS unsigned*)(lds + (bufoff) + ldsw + _i * 8192), 16, 0, 0); } while (0)
; #define PG8_WAIT_V(n) asm volatile("s_waitcnt vmcnt(" #n ")" ::: "memory")
; #define PG8_BAR __builtin_amdgcn_s_barrier()
; template <class Epi, class Sched>
; __device__ __forceinline__ void gemm_phase(LAS unsigned char* lds, const Gemm g, const Sched& S, const Epi& E) {
;     ...
;     PG8_STAGE(PG8_SB(0, 0), cB, voffB); PG8_STAGE(PG8_SB(0, 1), cB + hstep, voffB); PG8_STAGE(PG8_SA(0, 0), cA, voffA); PG8_STAGE(PG8_SA(0, 1), cA + hstep, voffA);
;     if (wr == 1) PG8_BAR;
;     PG8_WAIT_V(2); PG8_BAR;
;     PG8_STAGE(PG8_SB(1, 0), cB + kstep, voffB); PG8_STAGE(PG8_SA(1, 0), cA + kstep, voffA); PG8_STAGE(PG8_SB(1, 1), cB + hstep + kstep, voffB);
;     PG8_WAIT_V(6); PG8_BAR;
;     for (;;) {
;         const bool has_next = S.next(ui + 1, nxt);
;         const char* nA = has_next ? (const char*)g.A + (size_t)nxt.pm * tstep : cA; const char* nB = has_next ? (const char*)g.Bt + (size_t)nxt.pn * tstep : cB;
;         for (int t = 0; t < nt; t += 2) {
;             const bool last = (t == nt - 2);
;             const char* a1 = cA + (size_t)(t + 1) * kstep;
;             const char* a2 = last ? nA : cA + (size_t)(t + 2) * kstep; const char* b2 = last ? nB : cB + (size_t)(t + 2) * kstep;
.LBB0_443:
	v_readlane_b32 s38, v249, 8
	v_readlane_b32 s39, v249, 9
	s_add_u32 s46, s44, s38
	s_addc_u32 s47, s45, s39
	s_add_i32 m0, s5, 0x18000
	v_lshl_add_u64 v[2:3], v[2:3], 0, s[6:7]
	s_waitcnt vmcnt(2)
	s_barrier
	global_load_lds_dwordx4 v[2:3], off
	v_lshl_add_u64 v[2:3], v[4:5], 0, s[6:7]
	s_add_i32 m0, s5, 0x1a000
	s_add_i32 s55, s5, 0x8000
	global_load_lds_dwordx4 v[2:3], off
	v_lshl_add_u64 v[2:3], v[10:11], 0, s[6:7]
	s_mov_b32 m0, s55
	s_add_i32 s56, s5, 0xa000
	global_load_lds_dwordx4 v[2:3], off
	v_lshl_add_u64 v[2:3], v[12:13], 0, s[6:7]
	s_mov_b32 m0, s56
	s_lshr_b32 s1, s41, 26
	global_load_lds_dwordx4 v[2:3], off
	s_add_i32 m0, s5, 0x1c000
	v_lshl_add_u64 v[2:3], v[6:7], 0, s[6:7]
	v_mov_b64_e32 v[216:217], v[6:7]
	v_lshl_add_u64 v[2:3], v[8:9], 0, s[6:7]
	s_add_i32 m0, s5, 0x1e000
	s_add_i32 s1, s40, s1
	v_mov_b64_e32 v[238:239], v[8:9]
	v_and_b32_e32 v3, 15, v15
	v_and_b32_e32 v4, 48, v15
	v_lshlrev_b32_e32 v5, 2, v15
	s_ashr_i32 s57, s1, 6
	v_lshl_or_b32 v2, s36, 6, v3
	v_lshl_or_b32 v3, v3, 6, v4
	s_lshl_b32 s1, s36, 13
	v_and_b32_e32 v5, 32, v5
	v_bitop3_b32 v6, v3, s1, v5 bitop3:0xde
	s_lshl_b32 s1, s9, 5
	s_and_b32 s1, s1, 0x60
	s_lshl_b64 s[38:39], s[40:41], 9
	s_lshl_b32 s9, s1, 7
	s_cmp_gt_i32 s40, 63
	v_bitop3_b32 v160, v3, s9, v5 bitop3:0xde
	s_cselect_b64 s[40:41], -1, 0
	s_add_i32 s58, s57, -2
	v_ashrrev_i32_e32 v3, 31, v2
	s_cmpk_lt_u32 s8, 0x100
	v_lshlrev_b64 v[2:3], 11, v[2:3]
	s_cselect_b64 s[42:43], -1, 0
	v_lshl_add_u64 v[2:3], s[46:47], 0, v[2:3]
	s_lshl_b32 s36, s1, 1
	v_lshl_add_u64 v[2:3], v[2:3], 0, s[36:37]
	v_mov_b32_e32 v5, v1
	v_lshl_add_u64 v[2:3], v[2:3], 0, v[4:5]
	s_mov_b64 s[8:9], 0x6000000
	v_readlane_b32 s1, v248, 24
	v_lshl_add_u64 v[148:149], v[2:3], 0, s[8:9]
	s_add_u32 s1, s44, s1
	v_readlane_b32 s8, v248, 25
	s_addc_u32 s9, s45, s8
	v_add_u32_e32 v2, v20, v18
	s_add_u32 s8, s1, s18
	v_add_lshl_u32 v2, v2, v19, 1
	v_mov_b32_e32 v3, v1
	s_addc_u32 s9, s9, s19
	s_waitcnt vmcnt(4)
	v_lshl_add_u64 v[150:151], s[8:9], 0, v[2:3]
	v_add_u32_e32 v2, v17, v14
	v_add_lshl_u32 v2, v2, v16, 1
	v_lshl_add_u64 v[152:153], s[8:9], 0, v[2:3]
	s_mov_b32 s8, 0
	v_add_u32_e32 v161, 0, v6
	s_mov_b64 s[46:47], s[10:11]
	s_mov_b64 s[44:45], s[10:11]
	s_barrier
	s_branch .LBB0_446

; #define PG8_STAGE(bufoff, gbase, voff) do { _Pragma("unroll") for (int _i = 0; _i < 2; ++_i) \
;         __builtin_amdgcn_global_load_lds((const unsigned*)((const char*)(gbase) + (voff)[_i]), (LAS unsigned*)(lds + (bufoff) + ldsw + _i * 8192), 16, 0, 0); } while (0)
; #define PG8_LDA(dst, b, h) do { _Pragma("unroll") for (int m = 0; m < 4; ++m) _Pragma("unroll") for (int k = 0; k < 2; ++k) dst[m][k] = *(const LAS bf16x8*)(lds + PG8_SA(b, h) + aoff + m * 2048 + k * 1024); } while (0)
; #define PG8_LDB(dst, b, h) do { _Pragma("unroll") for (int n = 0; n < 2; ++n) _Pragma("unroll") for (int k = 0; k < 2; ++k) dst[n][k] = *(const LAS bf16x8*)(lds + PG8_SB(b, h) + boff + n * 2048 + k * 1024); } while (0)
; #define PG8_MMA(ai, bj, At, Bt) do { __builtin_amdgcn_s_setprio(1); _Pragma("unroll") for (int m = 0; m < 4; ++m) _Pragma("unroll") for (int n = 0; n < 2; ++n) _Pragma("unroll") for (int k = 0; k < 2; ++k) \
;         acc[ai][bj][m][n] = __builtin_amdgcn_mfma_f32_16x16x32_bf16(Bt[n][k], At[m][k], acc[ai][bj][m][n], 0, 0, 0); __builtin_amdgcn_s_setprio(0); } while (0)
; #define PG8_WAIT_V(n) asm volatile("s_waitcnt vmcnt(" #n ")" ::: "memory")
; #define PG8_WAIT_L(n) asm volatile("s_waitcnt lgkmcnt(" #n ")" ::: "memory")
; #define PG8_BAR __builtin_amdgcn_s_barrier()
; template <class Epi, class Sched>
; __device__ __forceinline__ void gemm_phase(LAS unsigned char* lds, const Gemm g, const Sched& S, const Epi& E) {
;     ...
;         for (int t = 0; t < nt; t += 2) {
;             const bool last = (t == nt - 2);
;             const char* a1 = cA + (size_t)(t + 1) * kstep;
;             const char* a2 = last ? nA : cA + (size_t)(t + 2) * kstep; const char* b2 = last ? nB : cB + (size_t)(t + 2) * kstep;
;             const char* a3 = a2 + kstep; const char* b3 = b2 + kstep;
;             if (last && has_next) S.a_ready(nxt);
;             PG8_LDB(B0, 0, 0); PG8_LDB(B1, 0, 1); PG8_SCHED; PG8_LDA(At, 0, 0); PG8_STAGE(PG8_SA(1, 1), a1 + hstep, voffA);
;             PG8_WAIT_V(8); PG8_WAIT_L(0); PG8_BAR; PG8_MMA(0, 0, At, B0); PG8_MMA(0, 1, At, B1); PG8_BAR; PG8_SCHED;
;             PG8_LDA(At, 0, 1); PG8_STAGE(PG8_SB(0, 0), b2, voffB); PG8_STAGE(PG8_SB(0, 1), b2 + hstep, voffB); PG8_STAGE(PG8_SA(0, 0), a2, voffA);
;             PG8_WAIT_V(8); PG8_WAIT_L(0); PG8_BAR; PG8_MMA(1, 0, At, B0); PG8_MMA(1, 1, At, B1); PG8_BAR; PG8_SCHED;
.LBB0_450:
	s_add_i32 s60, s50, 2
	s_add_u32 s48, s46, 0x100
	s_addc_u32 s49, s47, 0
	s_add_u32 s1, s9, s46
	s_addc_u32 s51, s36, s47
	s_cmp_eq_u32 s58, s50
	s_cselect_b32 s50, 0, s48
	s_cselect_b32 s61, 0, s49
	s_cselect_b32 s62, s44, s1
	s_cselect_b32 s63, s45, s51
	s_add_u32 s50, s2, s50
	s_addc_u32 s51, s3, s61
	s_add_i32 s1, 0, 0x10000
	s_add_i32 s61, 0, 0x14000
	v_add_u32_e32 v154, s1, v160
	v_add_u32_e32 v158, s61, v160
	ds_read_b128 v[130:133], v154
	ds_read_b128 v[134:137], v154 offset:1024
	ds_read_b128 v[138:141], v154 offset:2048
	ds_read_b128 v[154:157], v154 offset:3072
	ds_read_b128 v[162:165], v158
	ds_read_b128 v[166:169], v158 offset:1024
	ds_read_b128 v[170:173], v158 offset:2048
	ds_read_b128 v[174:177], v158 offset:3072
	v_lshl_add_u64 v[158:159], v[216:217], 0, s[6:7]
	s_add_i32 m0, s4, 0x1c000
	s_nop 0
	global_load_lds_dwordx4 v[158:159], off
	v_lshl_add_u64 v[158:159], v[238:239], 0, s[6:7]
	s_add_i32 m0, s4, 0x1e000
	s_nop 0
	global_load_lds_dwordx4 v[158:159], off
	v_lshl_add_u64 v[158:159], v[150:151], 0, s[46:47]
	s_add_i32 m0, s5, 0xc000
	ds_read_b128 v[178:181], v161
	ds_read_b128 v[182:185], v161 offset:1024
	ds_read_b128 v[192:195], v161 offset:2048
	ds_read_b128 v[196:199], v161 offset:3072
	ds_read_b128 v[200:203], v161 offset:4096
	ds_read_b128 v[204:207], v161 offset:5120
	ds_read_b128 v[208:211], v161 offset:6144
	ds_read_b128 v[212:215], v161 offset:7168
	global_load_lds_dwordx4 v[158:159], off
	v_lshl_add_u64 v[158:159], v[152:153], 0, s[46:47]
	s_add_i32 m0, s5, 0xe000
	s_nop 0
	global_load_lds_dwordx4 v[158:159], off
	s_waitcnt vmcnt(8)
	s_waitcnt lgkmcnt(0)
	s_barrier
	s_setprio 1
	s_waitcnt lgkmcnt(0)
	v_mfma_f32_16x16x32_bf16 v[122:125], v[130:133], v[178:181], v[122:125]
	v_mfma_f32_16x16x32_bf16 v[126:129], v[138:141], v[178:181], v[126:129]
	v_mfma_f32_16x16x32_bf16 v[110:113], v[130:133], v[192:195], v[110:113]
	v_mfma_f32_16x16x32_bf16 v[106:109], v[138:141], v[192:195], v[106:109]
	v_mfma_f32_16x16x32_bf16 v[94:97], v[130:133], v[200:203], v[94:97]
	v_mfma_f32_16x16x32_bf16 v[90:93], v[138:141], v[200:203], v[90:93]
	v_mfma_f32_16x16x32_bf16 v[78:81], v[130:133], v[208:211], v[78:81]
	v_mfma_f32_16x16x32_bf16 v[74:77], v[138:141], v[208:211], v[74:77]
	v_mfma_f32_16x16x32_bf16 v[122:125], v[134:137], v[182:185], v[122:125]
	v_mfma_f32_16x16x32_bf16 v[126:129], v[154:157], v[182:185], v[126:129]
	v_mfma_f32_16x16x32_bf16 v[110:113], v[134:137], v[196:199], v[110:113]
	v_mfma_f32_16x16x32_bf16 v[106:109], v[154:157], v[196:199], v[106:109]
	v_mfma_f32_16x16x32_bf16 v[94:97], v[134:137], v[204:207], v[94:97]
	v_mfma_f32_16x16x32_bf16 v[90:93], v[154:157], v[204:207], v[90:93]
	v_mfma_f32_16x16x32_bf16 v[78:81], v[134:137], v[212:215], v[78:81]
	v_mfma_f32_16x16x32_bf16 v[74:77], v[154:157], v[212:215], v[74:77]
	s_setprio 0
	s_setprio 1
	v_mfma_f32_16x16x32_bf16 v[118:121], v[162:165], v[178:181], v[118:121]
	v_mfma_f32_16x16x32_bf16 v[114:117], v[170:173], v[178:181], v[114:117]
	v_mfma_f32_16x16x32_bf16 v[102:105], v[162:165], v[192:195], v[102:105]
	v_mfma_f32_16x16x32_bf16 v[98:101], v[170:173], v[192:195], v[98:101]
	v_mfma_f32_16x16x32_bf16 v[86:89], v[162:165], v[200:203], v[86:89]
	v_mfma_f32_16x16x32_bf16 v[82:85], v[170:173], v[200:203], v[82:85]
	v_mfma_f32_16x16x32_bf16 v[70:73], v[162:165], v[208:211], v[70:73]
	v_mfma_f32_16x16x32_bf16 v[66:69], v[170:173], v[208:211], v[66:69]
	v_mfma_f32_16x16x32_bf16 v[118:121], v[166:169], v[182:185], v[118:121]
	v_mfma_f32_16x16x32_bf16 v[114:117], v[174:177], v[182:185], v[114:117]
	v_mfma_f32_16x16x32_bf16 v[102:105], v[166:169], v[196:199], v[102:105]
	v_mfma_f32_16x16x32_bf16 v[98:101], v[174:177], v[196:199], v[98:101]
	v_mfma_f32_16x16x32_bf16 v[86:89], v[166:169], v[204:207], v[86:89]
	v_mfma_f32_16x16x32_bf16 v[82:85], v[174:177], v[204:207], v[82:85]
	v_mfma_f32_16x16x32_bf16 v[70:73], v[166:169], v[212:215], v[70:73]
	v_mfma_f32_16x16x32_bf16 v[66:69], v[174:177], v[212:215], v[66:69]
	s_setprio 0
	s_barrier
	s_add_i32 s1, s1, s4
	v_lshl_add_u64 v[158:159], s[62:63], 0, v[0:1]
	s_mov_b32 m0, s1
	ds_read_b128 v[178:181], v161 offset:16384
	ds_read_b128 v[182:185], v161 offset:17408
	ds_read_b128 v[192:195], v161 offset:18432
	ds_read_b128 v[196:199], v161 offset:19456
	ds_read_b128 v[200:203], v161 offset:20480
	ds_read_b128 v[204:207], v161 offset:21504
	ds_read_b128 v[208:211], v161 offset:22528
	ds_read_b128 v[212:215], v161 offset:23552
	global_load_lds_dwordx4 v[158:159], off
	s_add_i32 m0, s1, 0x2000
	s_add_u32 s46, s62, s18
	v_lshl_add_u64 v[186:187], s[62:63], 0, v[142:143]
	s_addc_u32 s47, s63, s19
	s_add_i32 s1, s61, s4
	global_load_lds_dwordx4 v[186:187], off
	v_lshl_add_u64 v[216:217], s[46:47], 0, v[0:1]
	s_mov_b32 m0, s1
	v_lshl_add_u64 v[238:239], s[46:47], 0, v[142:143]
	s_add_i32 m0, s1, 0x2000
	v_lshl_add_u64 v[240:241], s[50:51], 0, v[146:147]
	s_mov_b32 m0, s5
	v_lshl_add_u64 v[244:245], s[50:51], 0, v[144:145]
	global_load_lds_dwordx4 v[240:241], off
	s_mov_b32 m0, s52
	s_nop 0
	global_load_lds_dwordx4 v[244:245], off
	s_waitcnt vmcnt(6)
	s_waitcnt lgkmcnt(0)
	s_barrier
; #define PG8_STAGE(bufoff, gbase, voff) do { _Pragma("unroll") for (int _i = 0; _i < 2; ++_i) \
;         __builtin_amdgcn_global_load_lds((const unsigned*)((const char*)(gbase) + (voff)[_i]), (LAS unsigned*)(lds + (bufoff) + ldsw + _i * 8192), 16, 0, 0); } while (0)
; #define PG8_LDA(dst, b, h) do { _Pragma("unroll") for (int m = 0; m < 4; ++m) _Pragma("unroll") for (int k = 0; k < 2; ++k) dst[m][k] = *(const LAS bf16x8*)(lds + PG8_SA(b, h) + aoff + m * 2048 + k * 1024); } while (0)
; #define PG8_LDB(dst, b, h) do { _Pragma("unroll") for (int n = 0; n < 2; ++n) _Pragma("unroll") for (int k = 0; k < 2; ++k) dst[n][k] = *(const LAS bf16x8*)(lds + PG8_SB(b, h) + boff + n * 2048 + k * 1024); } while (0)
; #define PG8_MMA(ai, bj, At, Bt) do { __builtin_amdgcn_s_setprio(1); _Pragma("unroll") for (int m = 0; m < 4; ++m) _Pragma("unroll") for (int n = 0; n < 2; ++n) _Pragma("unroll") for (int k = 0; k < 2; ++k) \
;         acc[ai][bj][m][n] = __builtin_amdgcn_mfma_f32_16x16x32_bf16(Bt[n][k], At[m][k], acc[ai][bj][m][n], 0, 0, 0); __builtin_amdgcn_s_setprio(0); } while (0)
; #define PG8_WAIT_V(n) asm volatile("s_waitcnt vmcnt(" #n ")" ::: "memory")
; #define PG8_WAIT_L(n) asm volatile("s_waitcnt lgkmcnt(" #n ")" ::: "memory")
; #define PG8_BAR __builtin_amdgcn_s_barrier()
; #define PG8_SCHED __builtin_amdgcn_sched_barrier(0)
; template <class Epi, class Sched>
; __device__ __forceinline__ void gemm_phase(LAS unsigned char* lds, const Gemm g, const Sched& S, const Epi& E) {
;     ...
;             PG8_WAIT_V(8); PG8_WAIT_L(0); PG8_BAR; PG8_MMA(1, 0, At, B0); PG8_MMA(1, 1, At, B1); PG8_BAR; PG8_SCHED;
;             PG8_LDB(B0, 1, 0); PG8_LDB(B1, 1, 1); PG8_SCHED; PG8_LDA(At, 1, 0); PG8_STAGE(PG8_SA(0, 1), a2 + hstep, voffA);
	s_setprio 1
	s_waitcnt lgkmcnt(0)
	v_mfma_f32_16x16x32_bf16 v[62:65], v[130:133], v[178:181], v[62:65]
	v_mfma_f32_16x16x32_bf16 v[58:61], v[138:141], v[178:181], v[58:61]
	v_mfma_f32_16x16x32_bf16 v[46:49], v[130:133], v[192:195], v[46:49]
	v_mfma_f32_16x16x32_bf16 v[42:45], v[138:141], v[192:195], v[42:45]
	v_mfma_f32_16x16x32_bf16 v[30:33], v[130:133], v[200:203], v[30:33]
	v_mfma_f32_16x16x32_bf16 v[26:29], v[138:141], v[200:203], v[26:29]
	v_mfma_f32_16x16x32_bf16 v[14:17], v[130:133], v[208:211], v[14:17]
	v_mfma_f32_16x16x32_bf16 v[10:13], v[138:141], v[208:211], v[10:13]
	v_mfma_f32_16x16x32_bf16 v[62:65], v[134:137], v[182:185], v[62:65]
	v_mfma_f32_16x16x32_bf16 v[58:61], v[154:157], v[182:185], v[58:61]
	v_mfma_f32_16x16x32_bf16 v[46:49], v[134:137], v[196:199], v[46:49]
	v_mfma_f32_16x16x32_bf16 v[42:45], v[154:157], v[196:199], v[42:45]
	v_mfma_f32_16x16x32_bf16 v[30:33], v[134:137], v[204:207], v[30:33]
	v_mfma_f32_16x16x32_bf16 v[26:29], v[154:157], v[204:207], v[26:29]
	v_mfma_f32_16x16x32_bf16 v[14:17], v[134:137], v[212:215], v[14:17]
	v_mfma_f32_16x16x32_bf16 v[10:13], v[154:157], v[212:215], v[10:13]
	s_setprio 0
	s_setprio 1
	v_mfma_f32_16x16x32_bf16 v[54:57], v[162:165], v[178:181], v[54:57]
	v_mfma_f32_16x16x32_bf16 v[50:53], v[170:173], v[178:181], v[50:53]
	v_mfma_f32_16x16x32_bf16 v[38:41], v[162:165], v[192:195], v[38:41]
	v_mfma_f32_16x16x32_bf16 v[34:37], v[170:173], v[192:195], v[34:37]
	v_mfma_f32_16x16x32_bf16 v[22:25], v[162:165], v[200:203], v[22:25]
	v_mfma_f32_16x16x32_bf16 v[18:21], v[170:173], v[200:203], v[18:21]
	v_mfma_f32_16x16x32_bf16 v[6:9], v[162:165], v[208:211], v[6:9]
	v_mfma_f32_16x16x32_bf16 v[2:5], v[170:173], v[208:211], v[2:5]
	v_mfma_f32_16x16x32_bf16 v[54:57], v[166:169], v[182:185], v[54:57]
	v_mfma_f32_16x16x32_bf16 v[50:53], v[174:177], v[182:185], v[50:53]
	v_mfma_f32_16x16x32_bf16 v[38:41], v[166:169], v[196:199], v[38:41]
	v_mfma_f32_16x16x32_bf16 v[34:37], v[174:177], v[196:199], v[34:37]
	v_mfma_f32_16x16x32_bf16 v[22:25], v[166:169], v[204:207], v[22:25]
	v_mfma_f32_16x16x32_bf16 v[18:21], v[174:177], v[204:207], v[18:21]
	v_mfma_f32_16x16x32_bf16 v[6:9], v[166:169], v[212:215], v[6:9]
	v_mfma_f32_16x16x32_bf16 v[2:5], v[174:177], v[212:215], v[2:5]
	s_setprio 0
	s_barrier
	s_add_i32 s1, 0, 0x18000
	s_add_i32 s61, 0, 0x1c000
	v_add_u32_e32 v154, s1, v160
	v_add_u32_e32 v174, s61, v160
	ds_read_b128 v[130:133], v154
	ds_read_b128 v[134:137], v154 offset:1024
	ds_read_b128 v[138:141], v154 offset:2048
	ds_read_b128 v[154:157], v154 offset:3072
	ds_read_b128 v[162:165], v174
	ds_read_b128 v[166:169], v174 offset:1024
	ds_read_b128 v[170:173], v174 offset:2048
	ds_read_b128 v[174:177], v174 offset:3072
	s_add_i32 m0, s4, 0x14000
	s_nop 0
	global_load_lds_dwordx4 v[216:217], off
	s_add_i32 m0, s4, 0x16000
	s_nop 0
	global_load_lds_dwordx4 v[238:239], off
	s_add_u32 s46, s50, s18
	s_addc_u32 s47, s51, s19
	s_mov_b32 m0, s53
	v_lshl_add_u64 v[246:247], s[46:47], 0, v[146:147]
	ds_read_b128 v[178:181], v161 offset:32768
	ds_read_b128 v[182:185], v161 offset:33792
	ds_read_b128 v[192:195], v161 offset:34816
	ds_read_b128 v[196:199], v161 offset:35840
	ds_read_b128 v[200:203], v161 offset:36864
	ds_read_b128 v[204:207], v161 offset:37888
	ds_read_b128 v[208:211], v161 offset:38912
	ds_read_b128 v[212:215], v161 offset:39936
	global_load_lds_dwordx4 v[246:247], off
	v_lshl_add_u64 v[246:247], s[46:47], 0, v[144:145]
	s_mov_b32 m0, s54
	s_nop 0
	global_load_lds_dwordx4 v[246:247], off
	s_waitcnt vmcnt(8)
	s_waitcnt lgkmcnt(0)
	s_barrier
; #define PG8_STAGE(bufoff, gbase, voff) do { _Pragma("unroll") for (int _i = 0; _i < 2; ++_i) \
;         __builtin_amdgcn_global_load_lds((const unsigned*)((const char*)(gbase) + (voff)[_i]), (LAS unsigned*)(lds + (bufoff) + ldsw + _i * 8192), 16, 0, 0); } while (0)
; #define PG8_LDA(dst, b, h) do { _Pragma("unroll") for (int m = 0; m < 4; ++m) _Pragma("unroll") for (int k = 0; k < 2; ++k) dst[m][k] = *(const LAS bf16x8*)(lds + PG8_SA(b, h) + aoff + m * 2048 + k * 1024); } while (0)
; #define PG8_MMA(ai, bj, At, Bt) do { __builtin_amdgcn_s_setprio(1); _Pragma("unroll") for (int m = 0; m < 4; ++m) _Pragma("unroll") for (int n = 0; n < 2; ++n) _Pragma("unroll") for (int k = 0; k < 2; ++k) \
;         acc[ai][bj][m][n] = __builtin_amdgcn_mfma_f32_16x16x32_bf16(Bt[n][k], At[m][k], acc[ai][bj][m][n], 0, 0, 0); __builtin_amdgcn_s_setprio(0); } while (0)
; #define PG8_WAIT_V(n) asm volatile("s_waitcnt vmcnt(" #n ")" ::: "memory")
; #define PG8_WAIT_L(n) asm volatile("s_waitcnt lgkmcnt(" #n ")" ::: "memory")
; #define PG8_BAR __builtin_amdgcn_s_barrier()
; #define PG8_SCHED __builtin_amdgcn_sched_barrier(0)
; template <class Epi, class Sched>
; __device__ __forceinline__ void gemm_phase(LAS unsigned char* lds, const Gemm g, const Sched& S, const Epi& E) {
;     ...
;             PG8_WAIT_V(8); PG8_WAIT_L(0); PG8_BAR; PG8_MMA(0, 0, At, B0); PG8_MMA(0, 1, At, B1); PG8_BAR; PG8_SCHED;
;             PG8_LDA(At, 1, 1); PG8_STAGE(PG8_SB(1, 0), b3, voffB); PG8_STAGE(PG8_SB(1, 1), b3 + hstep, voffB); PG8_STAGE(PG8_SA(1, 0), a3, voffA);
;             PG8_WAIT_V(8); PG8_WAIT_L(0); PG8_BAR; PG8_MMA(1, 0, At, B0); PG8_MMA(1, 1, At, B1); PG8_BAR; PG8_SCHED;
;         }
	s_setprio 1
	s_waitcnt lgkmcnt(0)
	v_mfma_f32_16x16x32_bf16 v[122:125], v[130:133], v[178:181], v[122:125]
	v_mfma_f32_16x16x32_bf16 v[126:129], v[138:141], v[178:181], v[126:129]
	v_mfma_f32_16x16x32_bf16 v[110:113], v[130:133], v[192:195], v[110:113]
	v_mfma_f32_16x16x32_bf16 v[106:109], v[138:141], v[192:195], v[106:109]
	v_mfma_f32_16x16x32_bf16 v[94:97], v[130:133], v[200:203], v[94:97]
	v_mfma_f32_16x16x32_bf16 v[90:93], v[138:141], v[200:203], v[90:93]
	v_mfma_f32_16x16x32_bf16 v[78:81], v[130:133], v[208:211], v[78:81]
	v_mfma_f32_16x16x32_bf16 v[74:77], v[138:141], v[208:211], v[74:77]
	v_mfma_f32_16x16x32_bf16 v[122:125], v[134:137], v[182:185], v[122:125]
	v_mfma_f32_16x16x32_bf16 v[126:129], v[154:157], v[182:185], v[126:129]
	v_mfma_f32_16x16x32_bf16 v[110:113], v[134:137], v[196:199], v[110:113]
	v_mfma_f32_16x16x32_bf16 v[106:109], v[154:157], v[196:199], v[106:109]
	v_mfma_f32_16x16x32_bf16 v[94:97], v[134:137], v[204:207], v[94:97]
	v_mfma_f32_16x16x32_bf16 v[90:93], v[154:157], v[204:207], v[90:93]
	v_mfma_f32_16x16x32_bf16 v[78:81], v[134:137], v[212:215], v[78:81]
	v_mfma_f32_16x16x32_bf16 v[74:77], v[154:157], v[212:215], v[74:77]
	s_setprio 0
	s_setprio 1
	v_mfma_f32_16x16x32_bf16 v[118:121], v[162:165], v[178:181], v[118:121]
	v_mfma_f32_16x16x32_bf16 v[114:117], v[170:173], v[178:181], v[114:117]
	v_mfma_f32_16x16x32_bf16 v[102:105], v[162:165], v[192:195], v[102:105]
	v_mfma_f32_16x16x32_bf16 v[98:101], v[170:173], v[192:195], v[98:101]
	v_mfma_f32_16x16x32_bf16 v[86:89], v[162:165], v[200:203], v[86:89]
	v_mfma_f32_16x16x32_bf16 v[82:85], v[170:173], v[200:203], v[82:85]
	v_mfma_f32_16x16x32_bf16 v[70:73], v[162:165], v[208:211], v[70:73]
	v_mfma_f32_16x16x32_bf16 v[66:69], v[170:173], v[208:211], v[66:69]
	v_mfma_f32_16x16x32_bf16 v[118:121], v[166:169], v[182:185], v[118:121]
	v_mfma_f32_16x16x32_bf16 v[114:117], v[174:177], v[182:185], v[114:117]
	v_mfma_f32_16x16x32_bf16 v[102:105], v[166:169], v[196:199], v[102:105]
	v_mfma_f32_16x16x32_bf16 v[98:101], v[174:177], v[196:199], v[98:101]
	v_mfma_f32_16x16x32_bf16 v[86:89], v[166:169], v[204:207], v[86:89]
	v_mfma_f32_16x16x32_bf16 v[82:85], v[174:177], v[204:207], v[82:85]
	v_mfma_f32_16x16x32_bf16 v[70:73], v[166:169], v[212:215], v[70:73]
	v_mfma_f32_16x16x32_bf16 v[66:69], v[174:177], v[212:215], v[66:69]
	s_setprio 0
	s_barrier
	s_add_i32 s1, s1, s4
	v_lshl_add_u64 v[158:159], v[158:159], 0, s[6:7]
	s_mov_b32 m0, s1
	ds_read_b128 v[178:181], v161 offset:49152
	ds_read_b128 v[182:185], v161 offset:50176
	ds_read_b128 v[192:195], v161 offset:51200
	ds_read_b128 v[196:199], v161 offset:52224
	ds_read_b128 v[200:203], v161 offset:53248
	ds_read_b128 v[204:207], v161 offset:54272
	ds_read_b128 v[208:211], v161 offset:55296
	ds_read_b128 v[212:215], v161 offset:56320
	global_load_lds_dwordx4 v[158:159], off
	v_lshl_add_u64 v[158:159], v[186:187], 0, s[6:7]
	s_add_i32 m0, s1, 0x2000
	s_add_i32 s1, s61, s4
	global_load_lds_dwordx4 v[158:159], off
	v_lshl_add_u64 v[158:159], v[216:217], 0, s[6:7]
	s_mov_b32 m0, s1
	s_nop 0
	v_lshl_add_u64 v[158:159], v[238:239], 0, s[6:7]
	s_add_i32 m0, s1, 0x2000
	s_nop 0
	v_lshl_add_u64 v[158:159], v[240:241], 0, s[6:7]
	s_mov_b32 m0, s55
	s_nop 0
	global_load_lds_dwordx4 v[158:159], off
	v_lshl_add_u64 v[158:159], v[244:245], 0, s[6:7]
	s_mov_b32 m0, s56
	s_nop 0
	global_load_lds_dwordx4 v[158:159], off
	s_waitcnt vmcnt(6)
	s_waitcnt lgkmcnt(0)
	s_barrier
	s_setprio 1
	s_waitcnt lgkmcnt(0)
	v_mfma_f32_16x16x32_bf16 v[62:65], v[130:133], v[178:181], v[62:65]
	v_mfma_f32_16x16x32_bf16 v[58:61], v[138:141], v[178:181], v[58:61]
	v_mfma_f32_16x16x32_bf16 v[46:49], v[130:133], v[192:195], v[46:49]
	v_mfma_f32_16x16x32_bf16 v[42:45], v[138:141], v[192:195], v[42:45]
	v_mfma_f32_16x16x32_bf16 v[30:33], v[130:133], v[200:203], v[30:33]
	v_mfma_f32_16x16x32_bf16 v[26:29], v[138:141], v[200:203], v[26:29]
	v_mfma_f32_16x16x32_bf16 v[14:17], v[130:133], v[208:211], v[14:17]
	v_mfma_f32_16x16x32_bf16 v[10:13], v[138:141], v[208:211], v[10:13]
	v_mfma_f32_16x16x32_bf16 v[62:65], v[134:137], v[182:185], v[62:65]
	v_mfma_f32_16x16x32_bf16 v[58:61], v[154:157], v[182:185], v[58:61]
	v_mfma_f32_16x16x32_bf16 v[46:49], v[134:137], v[196:199], v[46:49]
	v_mfma_f32_16x16x32_bf16 v[42:45], v[154:157], v[196:199], v[42:45]
	v_mfma_f32_16x16x32_bf16 v[30:33], v[134:137], v[204:207], v[30:33]
	v_mfma_f32_16x16x32_bf16 v[26:29], v[154:157], v[204:207], v[26:29]
	v_mfma_f32_16x16x32_bf16 v[14:17], v[134:137], v[212:215], v[14:17]
	v_mfma_f32_16x16x32_bf16 v[10:13], v[154:157], v[212:215], v[10:13]
	s_setprio 0
	s_setprio 1
	v_mfma_f32_16x16x32_bf16 v[54:57], v[162:165], v[178:181], v[54:57]
	v_mfma_f32_16x16x32_bf16 v[50:53], v[170:173], v[178:181], v[50:53]
	v_mfma_f32_16x16x32_bf16 v[38:41], v[162:165], v[192:195], v[38:41]
	v_mfma_f32_16x16x32_bf16 v[34:37], v[170:173], v[192:195], v[34:37]
	v_mfma_f32_16x16x32_bf16 v[22:25], v[162:165], v[200:203], v[22:25]
	v_mfma_f32_16x16x32_bf16 v[18:21], v[170:173], v[200:203], v[18:21]
	v_mfma_f32_16x16x32_bf16 v[6:9], v[162:165], v[208:211], v[6:9]
	v_mfma_f32_16x16x32_bf16 v[2:5], v[170:173], v[208:211], v[2:5]
	v_mfma_f32_16x16x32_bf16 v[54:57], v[166:169], v[182:185], v[54:57]
	v_mfma_f32_16x16x32_bf16 v[50:53], v[174:177], v[182:185], v[50:53]
	v_mfma_f32_16x16x32_bf16 v[38:41], v[166:169], v[196:199], v[38:41]
	v_mfma_f32_16x16x32_bf16 v[34:37], v[174:177], v[196:199], v[34:37]
	v_mfma_f32_16x16x32_bf16 v[22:25], v[166:169], v[204:207], v[22:25]
	v_mfma_f32_16x16x32_bf16 v[18:21], v[174:177], v[204:207], v[18:21]
	v_mfma_f32_16x16x32_bf16 v[6:9], v[166:169], v[212:215], v[6:9]
	v_mfma_f32_16x16x32_bf16 v[2:5], v[174:177], v[212:215], v[2:5]
	s_setprio 0
	s_barrier
	s_cmp_ge_i32 s60, s57
	s_mov_b64 s[46:47], s[48:49]
	s_mov_b32 s50, s60
	s_cbranch_scc0 .LBB0_450
